# weight conversion inner loop: both 32-row halves unrolled, 32 row loads (+32 scale loads) in flight before one wait
# speedup vs baseline: 1.0211x; 1.0027x over previous
; #define LAS __attribute__((address_space(3)))
; __device__ __forceinline__ void tr_item(const float* src, int ld_src, int k0, int c0, f16* dst, int ld_dst, int r0, int kc0, LAS float* scr, int lane, const float* gk) {
; #pragma unroll 16
;     for (int i = 0; i < 32; ++i) { const int kk = 2 * i + (lane >> 5); scr[kk * 33 + (lane & 31)] = __builtin_nontemporal_load(src + (size_t)(k0 + kk) * ld_src + c0 + (lane & 31)) * (gk ? gk[k0 + kk] : 1.0f); }
.LBB0_38:
	v_add_u32_e32 v16, s44, v11
	v_ashrrev_i32_e32 v17, 31, v16
	v_lshl_add_u64 v[82:83], v[14:15], 0, s[76:77]
	v_mov_b32_e32 v44, v16
	v_ashrrev_i32_e32 v45, 31, v44
	v_mul_lo_u32 v46, s66, v45
	v_mul_lo_u32 v47, s67, v44
	v_mad_u64_u32 v[80:81], s[58:59], s66, v44, 0
	v_add3_u32 v81, v81, v46, v47
	v_lshl_add_u64 v[80:81], v[80:81], 2, v[12:13]
	global_load_dword v48, v[80:81], off nt
	v_add_u32_e32 v44, 2, v16
	v_ashrrev_i32_e32 v45, 31, v44
	v_mul_lo_u32 v46, s66, v45
	v_mul_lo_u32 v47, s67, v44
	v_mad_u64_u32 v[80:81], s[58:59], s66, v44, 0
	v_add3_u32 v81, v81, v46, v47
	v_lshl_add_u64 v[80:81], v[80:81], 2, v[12:13]
	global_load_dword v49, v[80:81], off nt
	v_add_u32_e32 v44, 4, v16
	v_ashrrev_i32_e32 v45, 31, v44
	v_mul_lo_u32 v46, s66, v45
	v_mul_lo_u32 v47, s67, v44
	v_mad_u64_u32 v[80:81], s[58:59], s66, v44, 0
	v_add3_u32 v81, v81, v46, v47
	v_lshl_add_u64 v[80:81], v[80:81], 2, v[12:13]
	global_load_dword v50, v[80:81], off nt
	v_add_u32_e32 v44, 6, v16
	v_ashrrev_i32_e32 v45, 31, v44
	v_mul_lo_u32 v46, s66, v45
	v_mul_lo_u32 v47, s67, v44
	v_mad_u64_u32 v[80:81], s[58:59], s66, v44, 0
	v_add3_u32 v81, v81, v46, v47
	v_lshl_add_u64 v[80:81], v[80:81], 2, v[12:13]
	global_load_dword v51, v[80:81], off nt
	v_add_u32_e32 v44, 8, v16
	v_ashrrev_i32_e32 v45, 31, v44
	v_mul_lo_u32 v46, s66, v45
	v_mul_lo_u32 v47, s67, v44
	v_mad_u64_u32 v[80:81], s[58:59], s66, v44, 0
	v_add3_u32 v81, v81, v46, v47
	v_lshl_add_u64 v[80:81], v[80:81], 2, v[12:13]
	global_load_dword v52, v[80:81], off nt
	v_add_u32_e32 v44, 10, v16
	v_ashrrev_i32_e32 v45, 31, v44
	v_mul_lo_u32 v46, s66, v45
	v_mul_lo_u32 v47, s67, v44
	v_mad_u64_u32 v[80:81], s[58:59], s66, v44, 0
	v_add3_u32 v81, v81, v46, v47
	v_lshl_add_u64 v[80:81], v[80:81], 2, v[12:13]
	global_load_dword v53, v[80:81], off nt
	v_add_u32_e32 v44, 12, v16
	v_ashrrev_i32_e32 v45, 31, v44
	v_mul_lo_u32 v46, s66, v45
	v_mul_lo_u32 v47, s67, v44
	v_mad_u64_u32 v[80:81], s[58:59], s66, v44, 0
	v_add3_u32 v81, v81, v46, v47
	v_lshl_add_u64 v[80:81], v[80:81], 2, v[12:13]
	global_load_dword v54, v[80:81], off nt
	v_add_u32_e32 v44, 14, v16
	v_ashrrev_i32_e32 v45, 31, v44
	v_mul_lo_u32 v46, s66, v45
	v_mul_lo_u32 v47, s67, v44
	v_mad_u64_u32 v[80:81], s[58:59], s66, v44, 0
	v_add3_u32 v81, v81, v46, v47
	v_lshl_add_u64 v[80:81], v[80:81], 2, v[12:13]
	global_load_dword v55, v[80:81], off nt
	v_add_u32_e32 v44, 16, v16
	v_ashrrev_i32_e32 v45, 31, v44
	v_mul_lo_u32 v46, s66, v45
	v_mul_lo_u32 v47, s67, v44
	v_mad_u64_u32 v[80:81], s[58:59], s66, v44, 0
	v_add3_u32 v81, v81, v46, v47
	v_lshl_add_u64 v[80:81], v[80:81], 2, v[12:13]
	global_load_dword v56, v[80:81], off nt
	v_add_u32_e32 v44, 18, v16
	v_ashrrev_i32_e32 v45, 31, v44
	v_mul_lo_u32 v46, s66, v45
	v_mul_lo_u32 v47, s67, v44
	v_mad_u64_u32 v[80:81], s[58:59], s66, v44, 0
	v_add3_u32 v81, v81, v46, v47
	v_lshl_add_u64 v[80:81], v[80:81], 2, v[12:13]
	global_load_dword v57, v[80:81], off nt
	v_add_u32_e32 v44, 20, v16
	v_ashrrev_i32_e32 v45, 31, v44
	v_mul_lo_u32 v46, s66, v45
	v_mul_lo_u32 v47, s67, v44
	v_mad_u64_u32 v[80:81], s[58:59], s66, v44, 0
	v_add3_u32 v81, v81, v46, v47
	v_lshl_add_u64 v[80:81], v[80:81], 2, v[12:13]
	global_load_dword v58, v[80:81], off nt
	v_add_u32_e32 v44, 22, v16
	v_ashrrev_i32_e32 v45, 31, v44
	v_mul_lo_u32 v46, s66, v45
	v_mul_lo_u32 v47, s67, v44
	v_mad_u64_u32 v[80:81], s[58:59], s66, v44, 0
	v_add3_u32 v81, v81, v46, v47
	v_lshl_add_u64 v[80:81], v[80:81], 2, v[12:13]
	global_load_dword v59, v[80:81], off nt
	v_add_u32_e32 v44, 24, v16
	v_ashrrev_i32_e32 v45, 31, v44
	v_mul_lo_u32 v46, s66, v45
	v_mul_lo_u32 v47, s67, v44
	v_mad_u64_u32 v[80:81], s[58:59], s66, v44, 0
	v_add3_u32 v81, v81, v46, v47
	v_lshl_add_u64 v[80:81], v[80:81], 2, v[12:13]
	global_load_dword v60, v[80:81], off nt
	v_add_u32_e32 v44, 26, v16
	v_ashrrev_i32_e32 v45, 31, v44
	v_mul_lo_u32 v46, s66, v45
	v_mul_lo_u32 v47, s67, v44
	v_mad_u64_u32 v[80:81], s[58:59], s66, v44, 0
	v_add3_u32 v81, v81, v46, v47
	v_lshl_add_u64 v[80:81], v[80:81], 2, v[12:13]
	global_load_dword v61, v[80:81], off nt
	v_add_u32_e32 v44, 28, v16
	v_ashrrev_i32_e32 v45, 31, v44
	v_mul_lo_u32 v46, s66, v45
	v_mul_lo_u32 v47, s67, v44
	v_mad_u64_u32 v[80:81], s[58:59], s66, v44, 0
	v_add3_u32 v81, v81, v46, v47
	v_lshl_add_u64 v[80:81], v[80:81], 2, v[12:13]
	global_load_dword v62, v[80:81], off nt
	v_add_u32_e32 v44, 30, v16
	v_ashrrev_i32_e32 v45, 31, v44
	v_mul_lo_u32 v46, s66, v45
	v_mul_lo_u32 v47, s67, v44
	v_mad_u64_u32 v[80:81], s[58:59], s66, v44, 0
	v_add3_u32 v81, v81, v46, v47
	v_lshl_add_u64 v[80:81], v[80:81], 2, v[12:13]
	global_load_dword v63, v[80:81], off nt
	v_add_u32_e32 v44, 32, v16
	v_ashrrev_i32_e32 v45, 31, v44
	v_mul_lo_u32 v46, s66, v45
	v_mul_lo_u32 v47, s67, v44
	v_mad_u64_u32 v[80:81], s[58:59], s66, v44, 0
	v_add3_u32 v81, v81, v46, v47
	v_lshl_add_u64 v[80:81], v[80:81], 2, v[12:13]
	global_load_dword v64, v[80:81], off nt
	v_add_u32_e32 v44, 34, v16
	v_ashrrev_i32_e32 v45, 31, v44
	v_mul_lo_u32 v46, s66, v45
	v_mul_lo_u32 v47, s67, v44
	v_mad_u64_u32 v[80:81], s[58:59], s66, v44, 0
	v_add3_u32 v81, v81, v46, v47
	v_lshl_add_u64 v[80:81], v[80:81], 2, v[12:13]
	global_load_dword v65, v[80:81], off nt
	v_add_u32_e32 v44, 36, v16
	v_ashrrev_i32_e32 v45, 31, v44
	v_mul_lo_u32 v46, s66, v45
	v_mul_lo_u32 v47, s67, v44
	v_mad_u64_u32 v[80:81], s[58:59], s66, v44, 0
	v_add3_u32 v81, v81, v46, v47
	v_lshl_add_u64 v[80:81], v[80:81], 2, v[12:13]
	global_load_dword v66, v[80:81], off nt
	v_add_u32_e32 v44, 38, v16
	v_ashrrev_i32_e32 v45, 31, v44
	v_mul_lo_u32 v46, s66, v45
	v_mul_lo_u32 v47, s67, v44
	v_mad_u64_u32 v[80:81], s[58:59], s66, v44, 0
; #define LAS __attribute__((address_space(3)))
; __device__ __forceinline__ void tr_item(const float* src, int ld_src, int k0, int c0, f16* dst, int ld_dst, int r0, int kc0, LAS float* scr, int lane, const float* gk) {
; #pragma unroll 16
;     for (int i = 0; i < 32; ++i) { const int kk = 2 * i + (lane >> 5); scr[kk * 33 + (lane & 31)] = __builtin_nontemporal_load(src + (size_t)(k0 + kk) * ld_src + c0 + (lane & 31)) * (gk ? gk[k0 + kk] : 1.0f); }
	v_add3_u32 v81, v81, v46, v47
	v_lshl_add_u64 v[80:81], v[80:81], 2, v[12:13]
	global_load_dword v67, v[80:81], off nt
	v_add_u32_e32 v44, 40, v16
	v_ashrrev_i32_e32 v45, 31, v44
	v_mul_lo_u32 v46, s66, v45
	v_mul_lo_u32 v47, s67, v44
	v_mad_u64_u32 v[80:81], s[58:59], s66, v44, 0
	v_add3_u32 v81, v81, v46, v47
	v_lshl_add_u64 v[80:81], v[80:81], 2, v[12:13]
	global_load_dword v68, v[80:81], off nt
	v_add_u32_e32 v44, 42, v16
	v_ashrrev_i32_e32 v45, 31, v44
	v_mul_lo_u32 v46, s66, v45
	v_mul_lo_u32 v47, s67, v44
	v_mad_u64_u32 v[80:81], s[58:59], s66, v44, 0
	v_add3_u32 v81, v81, v46, v47
	v_lshl_add_u64 v[80:81], v[80:81], 2, v[12:13]
	global_load_dword v69, v[80:81], off nt
	v_add_u32_e32 v44, 44, v16
	v_ashrrev_i32_e32 v45, 31, v44
	v_mul_lo_u32 v46, s66, v45
	v_mul_lo_u32 v47, s67, v44
	v_mad_u64_u32 v[80:81], s[58:59], s66, v44, 0
	v_add3_u32 v81, v81, v46, v47
	v_lshl_add_u64 v[80:81], v[80:81], 2, v[12:13]
	global_load_dword v70, v[80:81], off nt
	v_add_u32_e32 v44, 46, v16
	v_ashrrev_i32_e32 v45, 31, v44
	v_mul_lo_u32 v46, s66, v45
	v_mul_lo_u32 v47, s67, v44
	v_mad_u64_u32 v[80:81], s[58:59], s66, v44, 0
	v_add3_u32 v81, v81, v46, v47
	v_lshl_add_u64 v[80:81], v[80:81], 2, v[12:13]
	global_load_dword v71, v[80:81], off nt
	v_add_u32_e32 v44, 48, v16
	v_ashrrev_i32_e32 v45, 31, v44
	v_mul_lo_u32 v46, s66, v45
	v_mul_lo_u32 v47, s67, v44
	v_mad_u64_u32 v[80:81], s[58:59], s66, v44, 0
	v_add3_u32 v81, v81, v46, v47
	v_lshl_add_u64 v[80:81], v[80:81], 2, v[12:13]
	global_load_dword v72, v[80:81], off nt
	v_add_u32_e32 v44, 50, v16
	v_ashrrev_i32_e32 v45, 31, v44
	v_mul_lo_u32 v46, s66, v45
	v_mul_lo_u32 v47, s67, v44
	v_mad_u64_u32 v[80:81], s[58:59], s66, v44, 0
	v_add3_u32 v81, v81, v46, v47
	v_lshl_add_u64 v[80:81], v[80:81], 2, v[12:13]
	global_load_dword v73, v[80:81], off nt
	v_add_u32_e32 v44, 52, v16
	v_ashrrev_i32_e32 v45, 31, v44
	v_mul_lo_u32 v46, s66, v45
	v_mul_lo_u32 v47, s67, v44
	v_mad_u64_u32 v[80:81], s[58:59], s66, v44, 0
	v_add3_u32 v81, v81, v46, v47
	v_lshl_add_u64 v[80:81], v[80:81], 2, v[12:13]
	global_load_dword v74, v[80:81], off nt
	v_add_u32_e32 v44, 54, v16
	v_ashrrev_i32_e32 v45, 31, v44
	v_mul_lo_u32 v46, s66, v45
	v_mul_lo_u32 v47, s67, v44
	v_mad_u64_u32 v[80:81], s[58:59], s66, v44, 0
	v_add3_u32 v81, v81, v46, v47
	v_lshl_add_u64 v[80:81], v[80:81], 2, v[12:13]
	global_load_dword v75, v[80:81], off nt
	v_add_u32_e32 v44, 56, v16
	v_ashrrev_i32_e32 v45, 31, v44
	v_mul_lo_u32 v46, s66, v45
	v_mul_lo_u32 v47, s67, v44
	v_mad_u64_u32 v[80:81], s[58:59], s66, v44, 0
	v_add3_u32 v81, v81, v46, v47
	v_lshl_add_u64 v[80:81], v[80:81], 2, v[12:13]
	global_load_dword v76, v[80:81], off nt
	v_add_u32_e32 v44, 58, v16
	v_ashrrev_i32_e32 v45, 31, v44
	v_mul_lo_u32 v46, s66, v45
	v_mul_lo_u32 v47, s67, v44
	v_mad_u64_u32 v[80:81], s[58:59], s66, v44, 0
	v_add3_u32 v81, v81, v46, v47
	v_lshl_add_u64 v[80:81], v[80:81], 2, v[12:13]
	global_load_dword v77, v[80:81], off nt
	v_add_u32_e32 v44, 60, v16
	v_ashrrev_i32_e32 v45, 31, v44
	v_mul_lo_u32 v46, s66, v45
	v_mul_lo_u32 v47, s67, v44
	v_mad_u64_u32 v[80:81], s[58:59], s66, v44, 0
	v_add3_u32 v81, v81, v46, v47
	v_lshl_add_u64 v[80:81], v[80:81], 2, v[12:13]
	global_load_dword v78, v[80:81], off nt
	v_add_u32_e32 v44, 62, v16
	v_ashrrev_i32_e32 v45, 31, v44
	v_mul_lo_u32 v46, s66, v45
	v_mul_lo_u32 v47, s67, v44
	v_mad_u64_u32 v[80:81], s[58:59], s66, v44, 0
	v_add3_u32 v81, v81, v46, v47
	v_lshl_add_u64 v[80:81], v[80:81], 2, v[12:13]
	global_load_dword v79, v[80:81], off nt
	v_mov_b32_e32 v84, 1.0
	v_mov_b32_e32 v85, 1.0
	v_mov_b32_e32 v86, 1.0
	v_mov_b32_e32 v87, 1.0
	v_mov_b32_e32 v88, 1.0
	v_mov_b32_e32 v89, 1.0
	v_mov_b32_e32 v90, 1.0
	v_mov_b32_e32 v91, 1.0
	v_mov_b32_e32 v92, 1.0
	v_mov_b32_e32 v93, 1.0
	v_mov_b32_e32 v94, 1.0
	v_mov_b32_e32 v95, 1.0
	v_mov_b32_e32 v96, 1.0
	v_mov_b32_e32 v97, 1.0
	v_mov_b32_e32 v98, 1.0
	v_mov_b32_e32 v99, 1.0
	v_mov_b32_e32 v100, 1.0
	v_mov_b32_e32 v101, 1.0
	v_mov_b32_e32 v102, 1.0
	v_mov_b32_e32 v103, 1.0
	v_mov_b32_e32 v104, 1.0
	v_mov_b32_e32 v105, 1.0
	v_mov_b32_e32 v106, 1.0
	v_mov_b32_e32 v107, 1.0
	v_mov_b32_e32 v108, 1.0
	v_mov_b32_e32 v109, 1.0
	v_mov_b32_e32 v110, 1.0
	v_mov_b32_e32 v111, 1.0
	v_mov_b32_e32 v112, 1.0
	v_mov_b32_e32 v113, 1.0
	v_mov_b32_e32 v114, 1.0
	v_mov_b32_e32 v115, 1.0
	v_cmp_ne_u32_e64 s[8:9], 1, v25
	s_andn2_b64 vcc, exec, s[72:73]
	s_cbranch_vccnz .Lwc_noscale
	v_lshl_add_u64 v[80:81], v[16:17], 2, s[62:63]
	global_load_dword v84, v[80:81], off
	global_load_dword v85, v[14:15], off offset:-112
	global_load_dword v86, v[14:15], off offset:-104
	global_load_dword v87, v[14:15], off offset:-96
	global_load_dword v88, v[14:15], off offset:-88
	global_load_dword v89, v[14:15], off offset:-80
	global_load_dword v90, v[14:15], off offset:-72
	global_load_dword v91, v[14:15], off offset:-64
	global_load_dword v92, v[14:15], off offset:-56
	global_load_dword v93, v[14:15], off offset:-48
	global_load_dword v94, v[14:15], off offset:-40
	global_load_dword v95, v[14:15], off offset:-32
	global_load_dword v96, v[14:15], off offset:-24
	global_load_dword v97, v[14:15], off offset:-16
	global_load_dword v98, v[14:15], off offset:-8
	global_load_dword v99, v[14:15], off
	global_load_dword v100, v[82:83], off offset:-120
	global_load_dword v101, v[82:83], off offset:-112
	global_load_dword v102, v[82:83], off offset:-104
	global_load_dword v103, v[82:83], off offset:-96
	global_load_dword v104, v[82:83], off offset:-88
	global_load_dword v105, v[82:83], off offset:-80
	global_load_dword v106, v[82:83], off offset:-72
	global_load_dword v107, v[82:83], off offset:-64
	global_load_dword v108, v[82:83], off offset:-56
	global_load_dword v109, v[82:83], off offset:-48
	global_load_dword v110, v[82:83], off offset:-40
	global_load_dword v111, v[82:83], off offset:-32
	global_load_dword v112, v[82:83], off offset:-24
	global_load_dword v113, v[82:83], off offset:-16
	global_load_dword v114, v[82:83], off offset:-8
	global_load_dword v115, v[82:83], off
; #define LAS __attribute__((address_space(3)))
; __device__ __forceinline__ void tr_item(const float* src, int ld_src, int k0, int c0, f16* dst, int ld_dst, int r0, int kc0, LAS float* scr, int lane, const float* gk) {
; #pragma unroll 16
;     for (int i = 0; i < 32; ++i) { const int kk = 2 * i + (lane >> 5); scr[kk * 33 + (lane & 31)] = __builtin_nontemporal_load(src + (size_t)(k0 + kk) * ld_src + c0 + (lane & 31)) * (gk ? gk[k0 + kk] : 1.0f); }
.Lwc_noscale:
	v_add_u32_e32 v45, 0x1080, v26
	s_waitcnt vmcnt(0)
	v_mul_f32_e32 v48, v48, v84
	ds_write_b32 v26, v48
	v_mul_f32_e32 v49, v49, v85
	ds_write_b32 v26, v49 offset:264
	v_mul_f32_e32 v50, v50, v86
	ds_write_b32 v26, v50 offset:528
	v_mul_f32_e32 v51, v51, v87
	ds_write_b32 v26, v51 offset:792
	v_mul_f32_e32 v52, v52, v88
	ds_write_b32 v26, v52 offset:1056
	v_mul_f32_e32 v53, v53, v89
	ds_write_b32 v26, v53 offset:1320
	v_mul_f32_e32 v54, v54, v90
	ds_write_b32 v26, v54 offset:1584
	v_mul_f32_e32 v55, v55, v91
	ds_write_b32 v26, v55 offset:1848
	v_mul_f32_e32 v56, v56, v92
	ds_write_b32 v26, v56 offset:2112
	v_mul_f32_e32 v57, v57, v93
	ds_write_b32 v26, v57 offset:2376
	v_mul_f32_e32 v58, v58, v94
	ds_write_b32 v26, v58 offset:2640
	v_mul_f32_e32 v59, v59, v95
	ds_write_b32 v26, v59 offset:2904
	v_mul_f32_e32 v60, v60, v96
	ds_write_b32 v26, v60 offset:3168
	v_mul_f32_e32 v61, v61, v97
	ds_write_b32 v26, v61 offset:3432
	v_mul_f32_e32 v62, v62, v98
	ds_write_b32 v26, v62 offset:3696
	v_mul_f32_e32 v63, v63, v99
	ds_write_b32 v26, v63 offset:3960
	v_mul_f32_e32 v64, v64, v100
	ds_write_b32 v45, v64
	v_mul_f32_e32 v65, v65, v101
	ds_write_b32 v45, v65 offset:264
	v_mul_f32_e32 v66, v66, v102
	ds_write_b32 v45, v66 offset:528
	v_mul_f32_e32 v67, v67, v103
	ds_write_b32 v45, v67 offset:792
	v_mul_f32_e32 v68, v68, v104
	ds_write_b32 v45, v68 offset:1056
	v_mul_f32_e32 v69, v69, v105
	ds_write_b32 v45, v69 offset:1320
	v_mul_f32_e32 v70, v70, v106
	ds_write_b32 v45, v70 offset:1584
	v_mul_f32_e32 v71, v71, v107
	ds_write_b32 v45, v71 offset:1848
	v_mul_f32_e32 v72, v72, v108
	ds_write_b32 v45, v72 offset:2112
	v_mul_f32_e32 v73, v73, v109
	ds_write_b32 v45, v73 offset:2376
	v_mul_f32_e32 v74, v74, v110
	ds_write_b32 v45, v74 offset:2640
	v_mul_f32_e32 v75, v75, v111
	ds_write_b32 v45, v75 offset:2904
	v_mul_f32_e32 v76, v76, v112
	ds_write_b32 v45, v76 offset:3168
	v_mul_f32_e32 v77, v77, v113
	ds_write_b32 v45, v77 offset:3432
	v_mul_f32_e32 v78, v78, v114
	ds_write_b32 v45, v78 offset:3696
	v_mul_f32_e32 v79, v79, v115
	ds_write_b32 v45, v79 offset:3960
	s_add_i32 s44, s44, 64
	v_add_u32_e32 v26, 0x2100, v26
	v_lshl_add_u64 v[14:15], v[82:83], 0, s[76:77]
	s_branch .LBB0_20
